# combined variant + virtual workgroup id rebuilt from the hardware XCC id (arrival rank within XCD * 8 + xcc) so XCD-chunked tile order matches real placement
# speedup vs baseline: 1.0034x; 1.0034x over previous
_Z8mega_fwd4Args:
	s_load_dwordx16 s[4:19], s[0:1], 0x80
	s_load_dwordx4 s[88:91], s[0:1], 0xc0
	v_writelane_b32 v251, s2, 0
	s_add_u32 s2, s0, 0xc8
	s_addc_u32 s3, s1, 0
	s_waitcnt lgkmcnt(0)
	v_writelane_b32 v251, s4, 1
	v_and_b32_e32 v183, 0x3ff, v0
	v_cmp_gt_u32_e32 vcc, 4, v183
	v_writelane_b32 v251, s5, 2
	v_writelane_b32 v251, s6, 3
	v_writelane_b32 v251, s7, 4
	v_writelane_b32 v251, s8, 5
	v_writelane_b32 v251, s9, 6
	v_writelane_b32 v251, s10, 7
	v_writelane_b32 v251, s11, 8
	v_writelane_b32 v251, s12, 9
	v_writelane_b32 v251, s13, 10
	v_writelane_b32 v251, s14, 11
	v_writelane_b32 v251, s15, 12
	v_writelane_b32 v251, s16, 13
	v_writelane_b32 v251, s17, 14
	v_writelane_b32 v251, s18, 15
	v_writelane_b32 v251, s19, 16
	v_writelane_b32 v251, s2, 17
	s_nop 1
	v_writelane_b32 v251, s3, 18
	s_and_saveexec_b64 s[2:3], vcc
	v_lshl_add_u32 v1, v183, 2, 0
	v_add_u32_e32 v1, 0x22000, v1
	v_mov_b32_e32 v2, 0
	ds_write_b32 v1, v2
	s_or_b64 exec, exec, s[2:3]
	s_load_dwordx16 s[4:19], s[0:1], 0x80
	s_waitcnt lgkmcnt(0)
	s_barrier
	s_getreg_b32 s4, hwreg(HW_REG_XCC_ID, 0, 4)
	s_add_u32 s2, s18, 0x1e700000
	s_addc_u32 s3, s19, 0
	s_and_b32 s8, s4, 15
	v_cmp_eq_u32_e64 s[6:7], 0, v183
	s_mov_b64 s[4:5], exec
	s_nop 0
	v_writelane_b32 v251, s6, 19
	s_nop 1
	v_writelane_b32 v251, s7, 20
	s_and_b64 s[6:7], s[4:5], s[6:7]
	s_mov_b64 exec, s[6:7]
	s_cbranch_execz .LBB0_5
	s_mov_b64 s[6:7], exec
	v_mbcnt_lo_u32_b32 v1, s6, 0
	v_mbcnt_hi_u32_b32 v1, s7, v1
	v_cmp_eq_u32_e32 vcc, 0, v1
	s_and_b64 s[10:11], exec, vcc
	s_mov_b64 exec, s[10:11]
	s_cbranch_execz .LBB0_5
	s_lshl_b32 s9, s8, 8
	s_bcnt1_i32_b64 s6, s[6:7]
	v_mov_b32_e32 v1, s9
	v_mov_b32_e32 v2, s6
	global_atomic_add v2, v1, v2, s[2:3] offset:1024 sc0
	s_waitcnt vmcnt(0)
	v_lshl_add_u32 v2, v2, 3, s8
	v_mov_b32_e32 v1, 0x2200c
	ds_write_b32 v1, v2
.LBB0_5:
	s_or_b64 exec, exec, s[4:5]
	s_waitcnt lgkmcnt(0)
	s_barrier
	s_cmp_lg_u32 s90, 0x100
	s_cbranch_scc1 .Lxccmap_skip
	v_mov_b32_e32 v2, 0x2200c
	ds_read_b32 v2, v2
	s_waitcnt lgkmcnt(0)
	v_readfirstlane_b32 s100, v2
	s_nop 3
	v_writelane_b32 v251, s100, 0
.Lxccmap_skip:
	s_cmp_ge_i32 s88, s89
	s_cbranch_scc0 .LBB0_6
	s_getpc_b64 s[98:99]
